# grid barrier: XCD leaders no longer issue (and wait for) the per-XCD release atomic that nothing reads any more
# baseline (speedup 1.0000x reference)
; __device__ __forceinline__ unsigned xb_ld(unsigned* p)              { return __hip_atomic_load(p, __ATOMIC_RELAXED, __HIP_MEMORY_SCOPE_AGENT); }
; __device__ __forceinline__ unsigned xb_add(unsigned* p, unsigned v) { return __hip_atomic_fetch_add(p, v, __ATOMIC_RELAXED, __HIP_MEMORY_SCOPE_AGENT); }
; #define XB_SPIN(cond, bar) do { unsigned _sp = 0; while (cond) { __builtin_amdgcn_s_sleep(1); \
;     if ((++_sp & 255u) == 0u) { if (xb_ld(&(bar)[XB_TMO])) break; if (_sp > XB_SPIN_CAP) { atomicAdd(&(bar)[XB_TMO], 1u); break; } } } } while (0)
; __device__ __forceinline__ void xcd_barrier(const XcdBarrier& b) {
;     ...
;             const unsigned og = xb_add(&bar[XB_TOP], 1u);
;             const unsigned tg = og / nx;
;             if (og + 1u == (tg + 1u) * nx) xb_add(&bar[XB_TOPGEN], 1u);
;             else XB_SPIN(xb_ld(&bar[XB_TOPGEN]) == tg, bar);
;             __builtin_amdgcn_fence(__ATOMIC_ACQUIRE, "agent");
;             xb_add(&bar[XB_XGEN(b.x)], 1u);
;             asm volatile("s_waitcnt vmcnt(0)" ::: "memory");
.LBB0_99:
	s_or_b64 exec, exec, s[8:9]
	s_mov_b64 s[8:9], exec
	v_mbcnt_lo_u32_b32 v1, s8, 0
	v_mbcnt_hi_u32_b32 v1, s9, v1
	v_cmp_eq_u32_e32 vcc, 0, v1
	s_waitcnt vmcnt(0)
	buffer_inv sc1
	s_and_saveexec_b64 s[10:11], vcc
	s_cbranch_execz .LBB0_101
	s_bcnt1_i32_b64 s8, s[8:9]
	v_mov_b32_e32 v1, 0x2000
	v_mov_b32_e32 v2, s8
	s_nop 0

; __device__ __forceinline__ unsigned xb_ld(unsigned* p)              { return __hip_atomic_load(p, __ATOMIC_RELAXED, __HIP_MEMORY_SCOPE_AGENT); }
; __device__ __forceinline__ unsigned xb_add(unsigned* p, unsigned v) { return __hip_atomic_fetch_add(p, v, __ATOMIC_RELAXED, __HIP_MEMORY_SCOPE_AGENT); }
; #define XB_SPIN(cond, bar) do { unsigned _sp = 0; while (cond) { __builtin_amdgcn_s_sleep(1); \
;     if ((++_sp & 255u) == 0u) { if (xb_ld(&(bar)[XB_TMO])) break; if (_sp > XB_SPIN_CAP) { atomicAdd(&(bar)[XB_TMO], 1u); break; } } } } while (0)
; __device__ __forceinline__ void xcd_barrier(const XcdBarrier& b) {
;     ...
;             const unsigned og = xb_add(&bar[XB_TOP], 1u);
;             const unsigned tg = og / nx;
;             if (og + 1u == (tg + 1u) * nx) xb_add(&bar[XB_TOPGEN], 1u);
;             else XB_SPIN(xb_ld(&bar[XB_TOPGEN]) == tg, bar);
;             __builtin_amdgcn_fence(__ATOMIC_ACQUIRE, "agent");
;             xb_add(&bar[XB_XGEN(b.x)], 1u);
;             asm volatile("s_waitcnt vmcnt(0)" ::: "memory");
.LBB0_172:
	s_or_b64 exec, exec, s[10:11]
	s_mov_b64 s[10:11], exec
	v_mbcnt_lo_u32_b32 v0, s10, 0
	v_mbcnt_hi_u32_b32 v0, s11, v0
	v_cmp_eq_u32_e32 vcc, 0, v0
	s_waitcnt vmcnt(0)
	buffer_inv sc1
	s_and_saveexec_b64 s[12:13], vcc
	s_cbranch_execz .LBB0_174
	s_bcnt1_i32_b64 s10, s[10:11]
	v_mov_b32_e32 v0, 0x2000
	v_mov_b32_e32 v1, s10
	s_nop 0
